# phase0 GEMV all loads in flight + top-k rank via XOR ds_swizzle compare (no readlane chains), on top of v51
# speedup vs baseline: 1.0234x; 1.0040x over previous
.LBB0_14:
	s_and_saveexec_b64 s[26:27], vcc
	s_cbranch_execz .LBB0_24
	s_ashr_i32 s19, s18, 31
	s_lshl_b64 s[30:31], s[18:19], 2
	s_add_u32 s34, s12, s30
	s_addc_u32 s35, s13, s31
	v_mul_u32_u24_e32 v166, 0x6000, v36
	v_lshl_add_u32 v166, v10, 2, v166
	v_cmp_gt_u32_e64 s[28:29], 16, v36
	global_load_dword v100, v166, s[34:35]
	s_add_u32 s34, s34, 0x7e000
	s_addc_u32 s35, s35, 0
	global_load_dword v101, v166, s[34:35]
	s_add_u32 s34, s34, 0x7e000
	s_addc_u32 s35, s35, 0
	global_load_dword v102, v166, s[34:35]
	s_add_u32 s34, s34, 0x7e000
	s_addc_u32 s35, s35, 0
	global_load_dword v103, v166, s[34:35]
	s_add_u32 s34, s34, 0x7e000
	s_addc_u32 s35, s35, 0
	global_load_dword v104, v166, s[34:35]
	s_add_u32 s34, s34, 0x7e000
	s_addc_u32 s35, s35, 0
	global_load_dword v105, v166, s[34:35]
	s_add_u32 s34, s34, 0x7e000
	s_addc_u32 s35, s35, 0
	global_load_dword v106, v166, s[34:35]
	s_add_u32 s34, s34, 0x7e000
	s_addc_u32 s35, s35, 0
	global_load_dword v107, v166, s[34:35]
	s_add_u32 s34, s34, 0x7e000
	s_addc_u32 s35, s35, 0
	global_load_dword v108, v166, s[34:35]
	s_add_u32 s34, s34, 0x7e000
	s_addc_u32 s35, s35, 0
	global_load_dword v109, v166, s[34:35]
	s_add_u32 s34, s34, 0x7e000
	s_addc_u32 s35, s35, 0
	global_load_dword v110, v166, s[34:35]
	s_add_u32 s34, s34, 0x7e000
	s_addc_u32 s35, s35, 0
	global_load_dword v111, v166, s[34:35]
	s_add_u32 s34, s34, 0x7e000
	s_addc_u32 s35, s35, 0
	global_load_dword v112, v166, s[34:35]
	s_add_u32 s34, s34, 0x7e000
	s_addc_u32 s35, s35, 0
	global_load_dword v113, v166, s[34:35]
	s_add_u32 s34, s34, 0x7e000
	s_addc_u32 s35, s35, 0
	global_load_dword v114, v166, s[34:35]
	s_add_u32 s34, s34, 0x7e000
	s_addc_u32 s35, s35, 0
	global_load_dword v115, v166, s[34:35]
	s_add_u32 s34, s34, 0x7e000
	s_addc_u32 s35, s35, 0
	global_load_dword v116, v166, s[34:35]
	s_add_u32 s34, s34, 0x7e000
	s_addc_u32 s35, s35, 0
	global_load_dword v117, v166, s[34:35]
	s_add_u32 s34, s34, 0x7e000
	s_addc_u32 s35, s35, 0
	global_load_dword v118, v166, s[34:35]
	s_add_u32 s34, s34, 0x7e000
	s_addc_u32 s35, s35, 0
	global_load_dword v119, v166, s[34:35]
	s_add_u32 s34, s34, 0x7e000
	s_addc_u32 s35, s35, 0
	global_load_dword v120, v166, s[34:35]
	s_add_u32 s34, s34, 0x7e000
	s_addc_u32 s35, s35, 0
	global_load_dword v121, v166, s[34:35]
	s_add_u32 s34, s34, 0x7e000
	s_addc_u32 s35, s35, 0
	global_load_dword v122, v166, s[34:35]
	s_add_u32 s34, s34, 0x7e000
	s_addc_u32 s35, s35, 0
	global_load_dword v123, v166, s[34:35]
	s_add_u32 s34, s34, 0x7e000
	s_addc_u32 s35, s35, 0
	global_load_dword v124, v166, s[34:35]
	s_add_u32 s34, s34, 0x7e000
	s_addc_u32 s35, s35, 0
	global_load_dword v125, v166, s[34:35]
	s_add_u32 s34, s34, 0x7e000
	s_addc_u32 s35, s35, 0
	global_load_dword v126, v166, s[34:35]
	s_add_u32 s34, s34, 0x7e000
	s_addc_u32 s35, s35, 0
	global_load_dword v127, v166, s[34:35]
	s_add_u32 s34, s34, 0x7e000
	s_addc_u32 s35, s35, 0
	global_load_dword v128, v166, s[34:35]
	s_add_u32 s34, s34, 0x7e000
	s_addc_u32 s35, s35, 0
	global_load_dword v129, v166, s[34:35]
	s_add_u32 s34, s34, 0x7e000
	s_addc_u32 s35, s35, 0
	global_load_dword v130, v166, s[34:35]
	s_add_u32 s34, s34, 0x7e000
	s_addc_u32 s35, s35, 0
	global_load_dword v131, v166, s[34:35]
	s_add_u32 s34, s34, 0x7e000
	s_addc_u32 s35, s35, 0
	global_load_dword v132, v166, s[34:35]
	s_add_u32 s34, s34, 0x7e000
	s_addc_u32 s35, s35, 0
	global_load_dword v133, v166, s[34:35]
	s_add_u32 s34, s34, 0x7e000
	s_addc_u32 s35, s35, 0
	global_load_dword v134, v166, s[34:35]
	s_add_u32 s34, s34, 0x7e000
	s_addc_u32 s35, s35, 0
	global_load_dword v135, v166, s[34:35]
	s_add_u32 s34, s34, 0x7e000
	s_addc_u32 s35, s35, 0
	global_load_dword v136, v166, s[34:35]
	s_add_u32 s34, s34, 0x7e000
	s_addc_u32 s35, s35, 0
	global_load_dword v137, v166, s[34:35]
	s_add_u32 s34, s34, 0x7e000
	s_addc_u32 s35, s35, 0
	global_load_dword v138, v166, s[34:35]
	s_add_u32 s34, s34, 0x7e000
	s_addc_u32 s35, s35, 0
	global_load_dword v139, v166, s[34:35]
	s_add_u32 s34, s34, 0x7e000
	s_addc_u32 s35, s35, 0
	global_load_dword v140, v166, s[34:35]
	s_add_u32 s34, s34, 0x7e000
	s_addc_u32 s35, s35, 0
	global_load_dword v141, v166, s[34:35]
	s_add_u32 s34, s34, 0x7e000
	s_addc_u32 s35, s35, 0
	global_load_dword v142, v166, s[34:35]
	s_add_u32 s34, s34, 0x7e000
	s_addc_u32 s35, s35, 0
	global_load_dword v143, v166, s[34:35]
	s_add_u32 s34, s34, 0x7e000
	s_addc_u32 s35, s35, 0
	global_load_dword v144, v166, s[34:35]
	s_add_u32 s34, s34, 0x7e000
	s_addc_u32 s35, s35, 0
	global_load_dword v145, v166, s[34:35]
	s_add_u32 s34, s34, 0x7e000
	s_addc_u32 s35, s35, 0
	global_load_dword v146, v166, s[34:35]
	s_add_u32 s34, s34, 0x7e000
	s_addc_u32 s35, s35, 0
	global_load_dword v147, v166, s[34:35]
	s_add_u32 s34, s34, 0x7e000
	s_addc_u32 s35, s35, 0
	s_and_saveexec_b64 s[6:7], s[28:29]
	s_cbranch_execz .Lp0_skip49
	global_load_dword v148, v166, s[34:35]
.Lp0_skip49:
	s_mov_b64 exec, s[6:7]
	v_mov_b32_e32 v6, 0
	v_mov_b32_e32 v7, 0
	v_mov_b32_e32 v8, 0
	v_mov_b32_e32 v9, 0
	v_mov_b32_e32 v2, 0
	v_mov_b32_e32 v3, 0
	v_mov_b32_e32 v4, 0
	v_mov_b32_e32 v5, 0
	v_mov_b32_e32 v167, v37
	ds_read2st64_b32 v[150:151], v167 offset1:16
	ds_read2st64_b32 v[152:153], v167 offset0:32 offset1:48
	ds_read2st64_b32 v[154:155], v167 offset0:64 offset1:80
	ds_read2st64_b32 v[156:157], v167 offset0:96 offset1:112
	v_add_u32_e32 v168, 84, v37
	ds_read2st64_b32 v[158:159], v168 offset1:16
	ds_read2st64_b32 v[160:161], v168 offset0:32 offset1:48
	ds_read2st64_b32 v[162:163], v168 offset0:64 offset1:80
	ds_read2st64_b32 v[164:165], v168 offset0:96 offset1:112
	s_waitcnt vmcnt(47) lgkmcnt(4)
	v_fma_f32 v6, v100, v150, v6
	v_fma_f32 v7, v100, v151, v7
	v_fma_f32 v8, v100, v152, v8
	v_fma_f32 v9, v100, v153, v9
	v_fma_f32 v2, v100, v154, v2
	v_fma_f32 v3, v100, v155, v3
	v_fma_f32 v4, v100, v156, v4
	v_fma_f32 v5, v100, v157, v5
	v_add_u32_e32 v167, 168, v37
	ds_read2st64_b32 v[150:151], v167 offset1:16
	ds_read2st64_b32 v[152:153], v167 offset0:32 offset1:48
	ds_read2st64_b32 v[154:155], v167 offset0:64 offset1:80
	ds_read2st64_b32 v[156:157], v167 offset0:96 offset1:112
	s_waitcnt vmcnt(46) lgkmcnt(4)
	v_fma_f32 v6, v101, v158, v6
	v_fma_f32 v7, v101, v159, v7
	v_fma_f32 v8, v101, v160, v8
	v_fma_f32 v9, v101, v161, v9
	v_fma_f32 v2, v101, v162, v2
	v_fma_f32 v3, v101, v163, v3
	v_fma_f32 v4, v101, v164, v4
	v_fma_f32 v5, v101, v165, v5
	v_add_u32_e32 v168, 252, v37
	ds_read2st64_b32 v[158:159], v168 offset1:16
	ds_read2st64_b32 v[160:161], v168 offset0:32 offset1:48
	ds_read2st64_b32 v[162:163], v168 offset0:64 offset1:80
	ds_read2st64_b32 v[164:165], v168 offset0:96 offset1:112
	s_waitcnt vmcnt(45) lgkmcnt(4)
	v_fma_f32 v6, v102, v150, v6
	v_fma_f32 v7, v102, v151, v7
	v_fma_f32 v8, v102, v152, v8
	v_fma_f32 v9, v102, v153, v9
	v_fma_f32 v2, v102, v154, v2
	v_fma_f32 v3, v102, v155, v3
	v_fma_f32 v4, v102, v156, v4
	v_fma_f32 v5, v102, v157, v5
	v_add_u32_e32 v167, 336, v37
	ds_read2st64_b32 v[150:151], v167 offset1:16
	ds_read2st64_b32 v[152:153], v167 offset0:32 offset1:48
	ds_read2st64_b32 v[154:155], v167 offset0:64 offset1:80
	ds_read2st64_b32 v[156:157], v167 offset0:96 offset1:112
	s_waitcnt vmcnt(44) lgkmcnt(4)
	v_fma_f32 v6, v103, v158, v6
	v_fma_f32 v7, v103, v159, v7
	v_fma_f32 v8, v103, v160, v8
	v_fma_f32 v9, v103, v161, v9
	v_fma_f32 v2, v103, v162, v2
	v_fma_f32 v3, v103, v163, v3
	v_fma_f32 v4, v103, v164, v4
	v_fma_f32 v5, v103, v165, v5
	v_add_u32_e32 v168, 420, v37
	ds_read2st64_b32 v[158:159], v168 offset1:16
	ds_read2st64_b32 v[160:161], v168 offset0:32 offset1:48
	ds_read2st64_b32 v[162:163], v168 offset0:64 offset1:80
	ds_read2st64_b32 v[164:165], v168 offset0:96 offset1:112
	s_waitcnt vmcnt(43) lgkmcnt(4)
	v_fma_f32 v6, v104, v150, v6
	v_fma_f32 v7, v104, v151, v7
	v_fma_f32 v8, v104, v152, v8
	v_fma_f32 v9, v104, v153, v9
	v_fma_f32 v2, v104, v154, v2
	v_fma_f32 v3, v104, v155, v3
	v_fma_f32 v4, v104, v156, v4
	v_fma_f32 v5, v104, v157, v5
	v_add_u32_e32 v167, 504, v37
	ds_read2st64_b32 v[150:151], v167 offset1:16
	ds_read2st64_b32 v[152:153], v167 offset0:32 offset1:48
	ds_read2st64_b32 v[154:155], v167 offset0:64 offset1:80
	ds_read2st64_b32 v[156:157], v167 offset0:96 offset1:112
	s_waitcnt vmcnt(42) lgkmcnt(4)
	v_fma_f32 v6, v105, v158, v6
	v_fma_f32 v7, v105, v159, v7
	v_fma_f32 v8, v105, v160, v8
	v_fma_f32 v9, v105, v161, v9
	v_fma_f32 v2, v105, v162, v2
	v_fma_f32 v3, v105, v163, v3
	v_fma_f32 v4, v105, v164, v4
	v_fma_f32 v5, v105, v165, v5
	v_add_u32_e32 v168, 588, v37
	ds_read2st64_b32 v[158:159], v168 offset1:16
	ds_read2st64_b32 v[160:161], v168 offset0:32 offset1:48
	ds_read2st64_b32 v[162:163], v168 offset0:64 offset1:80
	ds_read2st64_b32 v[164:165], v168 offset0:96 offset1:112
	s_waitcnt vmcnt(41) lgkmcnt(4)
	v_fma_f32 v6, v106, v150, v6
	v_fma_f32 v7, v106, v151, v7
	v_fma_f32 v8, v106, v152, v8
	v_fma_f32 v9, v106, v153, v9
	v_fma_f32 v2, v106, v154, v2
	v_fma_f32 v3, v106, v155, v3
	v_fma_f32 v4, v106, v156, v4
	v_fma_f32 v5, v106, v157, v5
	v_add_u32_e32 v167, 672, v37
	ds_read2st64_b32 v[150:151], v167 offset1:16
	ds_read2st64_b32 v[152:153], v167 offset0:32 offset1:48
	ds_read2st64_b32 v[154:155], v167 offset0:64 offset1:80
	ds_read2st64_b32 v[156:157], v167 offset0:96 offset1:112
	s_waitcnt vmcnt(40) lgkmcnt(4)
	v_fma_f32 v6, v107, v158, v6
	v_fma_f32 v7, v107, v159, v7
	v_fma_f32 v8, v107, v160, v8
	v_fma_f32 v9, v107, v161, v9
	v_fma_f32 v2, v107, v162, v2
	v_fma_f32 v3, v107, v163, v3
	v_fma_f32 v4, v107, v164, v4
	v_fma_f32 v5, v107, v165, v5
	v_add_u32_e32 v168, 756, v37
	ds_read2st64_b32 v[158:159], v168 offset1:16
	ds_read2st64_b32 v[160:161], v168 offset0:32 offset1:48
	ds_read2st64_b32 v[162:163], v168 offset0:64 offset1:80
	ds_read2st64_b32 v[164:165], v168 offset0:96 offset1:112
	s_waitcnt vmcnt(39) lgkmcnt(4)
	v_fma_f32 v6, v108, v150, v6
	v_fma_f32 v7, v108, v151, v7
	v_fma_f32 v8, v108, v152, v8
	v_fma_f32 v9, v108, v153, v9
	v_fma_f32 v2, v108, v154, v2
	v_fma_f32 v3, v108, v155, v3
	v_fma_f32 v4, v108, v156, v4
	v_fma_f32 v5, v108, v157, v5
	v_add_u32_e32 v167, 840, v37
	ds_read2st64_b32 v[150:151], v167 offset1:16
	ds_read2st64_b32 v[152:153], v167 offset0:32 offset1:48
	ds_read2st64_b32 v[154:155], v167 offset0:64 offset1:80
	ds_read2st64_b32 v[156:157], v167 offset0:96 offset1:112
	s_waitcnt vmcnt(38) lgkmcnt(4)
	v_fma_f32 v6, v109, v158, v6
	v_fma_f32 v7, v109, v159, v7
	v_fma_f32 v8, v109, v160, v8
	v_fma_f32 v9, v109, v161, v9
	v_fma_f32 v2, v109, v162, v2
	v_fma_f32 v3, v109, v163, v3
	v_fma_f32 v4, v109, v164, v4
	v_fma_f32 v5, v109, v165, v5
	v_add_u32_e32 v168, 924, v37
	ds_read2st64_b32 v[158:159], v168 offset1:16
	ds_read2st64_b32 v[160:161], v168 offset0:32 offset1:48
	ds_read2st64_b32 v[162:163], v168 offset0:64 offset1:80
	ds_read2st64_b32 v[164:165], v168 offset0:96 offset1:112
	s_waitcnt vmcnt(37) lgkmcnt(4)
	v_fma_f32 v6, v110, v150, v6
	v_fma_f32 v7, v110, v151, v7
	v_fma_f32 v8, v110, v152, v8
	v_fma_f32 v9, v110, v153, v9
	v_fma_f32 v2, v110, v154, v2
	v_fma_f32 v3, v110, v155, v3
	v_fma_f32 v4, v110, v156, v4
	v_fma_f32 v5, v110, v157, v5
	v_add_u32_e32 v167, 1008, v37
	ds_read2st64_b32 v[150:151], v167 offset1:16
	ds_read2st64_b32 v[152:153], v167 offset0:32 offset1:48
	ds_read2st64_b32 v[154:155], v167 offset0:64 offset1:80
	ds_read2st64_b32 v[156:157], v167 offset0:96 offset1:112
	s_waitcnt vmcnt(36) lgkmcnt(4)
	v_fma_f32 v6, v111, v158, v6
	v_fma_f32 v7, v111, v159, v7
	v_fma_f32 v8, v111, v160, v8
	v_fma_f32 v9, v111, v161, v9
	v_fma_f32 v2, v111, v162, v2
	v_fma_f32 v3, v111, v163, v3
	v_fma_f32 v4, v111, v164, v4
	v_fma_f32 v5, v111, v165, v5
	v_add_u32_e32 v168, 1092, v37
	ds_read2st64_b32 v[158:159], v168 offset1:16
	ds_read2st64_b32 v[160:161], v168 offset0:32 offset1:48
	ds_read2st64_b32 v[162:163], v168 offset0:64 offset1:80
	ds_read2st64_b32 v[164:165], v168 offset0:96 offset1:112
	s_waitcnt vmcnt(35) lgkmcnt(4)
	v_fma_f32 v6, v112, v150, v6
	v_fma_f32 v7, v112, v151, v7
	v_fma_f32 v8, v112, v152, v8
	v_fma_f32 v9, v112, v153, v9
	v_fma_f32 v2, v112, v154, v2
	v_fma_f32 v3, v112, v155, v3
	v_fma_f32 v4, v112, v156, v4
	v_fma_f32 v5, v112, v157, v5
	v_add_u32_e32 v167, 1176, v37
	ds_read2st64_b32 v[150:151], v167 offset1:16
	ds_read2st64_b32 v[152:153], v167 offset0:32 offset1:48
	ds_read2st64_b32 v[154:155], v167 offset0:64 offset1:80
	ds_read2st64_b32 v[156:157], v167 offset0:96 offset1:112
	s_waitcnt vmcnt(34) lgkmcnt(4)
	v_fma_f32 v6, v113, v158, v6
	v_fma_f32 v7, v113, v159, v7
	v_fma_f32 v8, v113, v160, v8
	v_fma_f32 v9, v113, v161, v9
	v_fma_f32 v2, v113, v162, v2
	v_fma_f32 v3, v113, v163, v3
	v_fma_f32 v4, v113, v164, v4
	v_fma_f32 v5, v113, v165, v5
	v_add_u32_e32 v168, 1260, v37
	ds_read2st64_b32 v[158:159], v168 offset1:16
	ds_read2st64_b32 v[160:161], v168 offset0:32 offset1:48
	ds_read2st64_b32 v[162:163], v168 offset0:64 offset1:80
	ds_read2st64_b32 v[164:165], v168 offset0:96 offset1:112
	s_waitcnt vmcnt(33) lgkmcnt(4)
	v_fma_f32 v6, v114, v150, v6
	v_fma_f32 v7, v114, v151, v7
	v_fma_f32 v8, v114, v152, v8
	v_fma_f32 v9, v114, v153, v9
	v_fma_f32 v2, v114, v154, v2
	v_fma_f32 v3, v114, v155, v3
	v_fma_f32 v4, v114, v156, v4
	v_fma_f32 v5, v114, v157, v5
	v_add_u32_e32 v167, 1344, v37
	ds_read2st64_b32 v[150:151], v167 offset1:16
	ds_read2st64_b32 v[152:153], v167 offset0:32 offset1:48
	ds_read2st64_b32 v[154:155], v167 offset0:64 offset1:80
	ds_read2st64_b32 v[156:157], v167 offset0:96 offset1:112
	s_waitcnt vmcnt(32) lgkmcnt(4)
	v_fma_f32 v6, v115, v158, v6
	v_fma_f32 v7, v115, v159, v7
	v_fma_f32 v8, v115, v160, v8
	v_fma_f32 v9, v115, v161, v9
	v_fma_f32 v2, v115, v162, v2
	v_fma_f32 v3, v115, v163, v3
	v_fma_f32 v4, v115, v164, v4
	v_fma_f32 v5, v115, v165, v5
	v_add_u32_e32 v168, 1428, v37
	ds_read2st64_b32 v[158:159], v168 offset1:16
	ds_read2st64_b32 v[160:161], v168 offset0:32 offset1:48
	ds_read2st64_b32 v[162:163], v168 offset0:64 offset1:80
	ds_read2st64_b32 v[164:165], v168 offset0:96 offset1:112
	s_waitcnt vmcnt(31) lgkmcnt(4)
	v_fma_f32 v6, v116, v150, v6
	v_fma_f32 v7, v116, v151, v7
	v_fma_f32 v8, v116, v152, v8
	v_fma_f32 v9, v116, v153, v9
	v_fma_f32 v2, v116, v154, v2
	v_fma_f32 v3, v116, v155, v3
	v_fma_f32 v4, v116, v156, v4
	v_fma_f32 v5, v116, v157, v5
	v_add_u32_e32 v167, 1512, v37
	ds_read2st64_b32 v[150:151], v167 offset1:16
	ds_read2st64_b32 v[152:153], v167 offset0:32 offset1:48
	ds_read2st64_b32 v[154:155], v167 offset0:64 offset1:80
	ds_read2st64_b32 v[156:157], v167 offset0:96 offset1:112
	s_waitcnt vmcnt(30) lgkmcnt(4)
	v_fma_f32 v6, v117, v158, v6
	v_fma_f32 v7, v117, v159, v7
	v_fma_f32 v8, v117, v160, v8
	v_fma_f32 v9, v117, v161, v9
	v_fma_f32 v2, v117, v162, v2
	v_fma_f32 v3, v117, v163, v3
	v_fma_f32 v4, v117, v164, v4
	v_fma_f32 v5, v117, v165, v5
	v_add_u32_e32 v168, 1596, v37
	ds_read2st64_b32 v[158:159], v168 offset1:16
	ds_read2st64_b32 v[160:161], v168 offset0:32 offset1:48
	ds_read2st64_b32 v[162:163], v168 offset0:64 offset1:80
	ds_read2st64_b32 v[164:165], v168 offset0:96 offset1:112
	s_waitcnt vmcnt(29) lgkmcnt(4)
	v_fma_f32 v6, v118, v150, v6
	v_fma_f32 v7, v118, v151, v7
	v_fma_f32 v8, v118, v152, v8
	v_fma_f32 v9, v118, v153, v9
	v_fma_f32 v2, v118, v154, v2
	v_fma_f32 v3, v118, v155, v3
	v_fma_f32 v4, v118, v156, v4
	v_fma_f32 v5, v118, v157, v5
	v_add_u32_e32 v167, 1680, v37
	ds_read2st64_b32 v[150:151], v167 offset1:16
	ds_read2st64_b32 v[152:153], v167 offset0:32 offset1:48
	ds_read2st64_b32 v[154:155], v167 offset0:64 offset1:80
	ds_read2st64_b32 v[156:157], v167 offset0:96 offset1:112
	s_waitcnt vmcnt(28) lgkmcnt(4)
	v_fma_f32 v6, v119, v158, v6
	v_fma_f32 v7, v119, v159, v7
	v_fma_f32 v8, v119, v160, v8
	v_fma_f32 v9, v119, v161, v9
	v_fma_f32 v2, v119, v162, v2
	v_fma_f32 v3, v119, v163, v3
	v_fma_f32 v4, v119, v164, v4
	v_fma_f32 v5, v119, v165, v5
	v_add_u32_e32 v168, 1764, v37
	ds_read2st64_b32 v[158:159], v168 offset1:16
	ds_read2st64_b32 v[160:161], v168 offset0:32 offset1:48
	ds_read2st64_b32 v[162:163], v168 offset0:64 offset1:80
	ds_read2st64_b32 v[164:165], v168 offset0:96 offset1:112
	s_waitcnt vmcnt(27) lgkmcnt(4)
	v_fma_f32 v6, v120, v150, v6
	v_fma_f32 v7, v120, v151, v7
	v_fma_f32 v8, v120, v152, v8
	v_fma_f32 v9, v120, v153, v9
	v_fma_f32 v2, v120, v154, v2
	v_fma_f32 v3, v120, v155, v3
	v_fma_f32 v4, v120, v156, v4
	v_fma_f32 v5, v120, v157, v5
	v_add_u32_e32 v167, 1848, v37
	ds_read2st64_b32 v[150:151], v167 offset1:16
	ds_read2st64_b32 v[152:153], v167 offset0:32 offset1:48
	ds_read2st64_b32 v[154:155], v167 offset0:64 offset1:80
	ds_read2st64_b32 v[156:157], v167 offset0:96 offset1:112
	s_waitcnt vmcnt(26) lgkmcnt(4)
	v_fma_f32 v6, v121, v158, v6
	v_fma_f32 v7, v121, v159, v7
	v_fma_f32 v8, v121, v160, v8
	v_fma_f32 v9, v121, v161, v9
	v_fma_f32 v2, v121, v162, v2
	v_fma_f32 v3, v121, v163, v3
	v_fma_f32 v4, v121, v164, v4
	v_fma_f32 v5, v121, v165, v5
	v_add_u32_e32 v168, 1932, v37
	ds_read2st64_b32 v[158:159], v168 offset1:16
	ds_read2st64_b32 v[160:161], v168 offset0:32 offset1:48
	ds_read2st64_b32 v[162:163], v168 offset0:64 offset1:80
	ds_read2st64_b32 v[164:165], v168 offset0:96 offset1:112
	s_waitcnt vmcnt(25) lgkmcnt(4)
	v_fma_f32 v6, v122, v150, v6
	v_fma_f32 v7, v122, v151, v7
	v_fma_f32 v8, v122, v152, v8
	v_fma_f32 v9, v122, v153, v9
	v_fma_f32 v2, v122, v154, v2
	v_fma_f32 v3, v122, v155, v3
	v_fma_f32 v4, v122, v156, v4
	v_fma_f32 v5, v122, v157, v5
	v_add_u32_e32 v167, 2016, v37
	ds_read2st64_b32 v[150:151], v167 offset1:16
	ds_read2st64_b32 v[152:153], v167 offset0:32 offset1:48
	ds_read2st64_b32 v[154:155], v167 offset0:64 offset1:80
	ds_read2st64_b32 v[156:157], v167 offset0:96 offset1:112
	s_waitcnt vmcnt(24) lgkmcnt(4)
	v_fma_f32 v6, v123, v158, v6
	v_fma_f32 v7, v123, v159, v7
	v_fma_f32 v8, v123, v160, v8
	v_fma_f32 v9, v123, v161, v9
	v_fma_f32 v2, v123, v162, v2
	v_fma_f32 v3, v123, v163, v3
	v_fma_f32 v4, v123, v164, v4
	v_fma_f32 v5, v123, v165, v5
	v_add_u32_e32 v168, 2100, v37
	ds_read2st64_b32 v[158:159], v168 offset1:16
	ds_read2st64_b32 v[160:161], v168 offset0:32 offset1:48
	ds_read2st64_b32 v[162:163], v168 offset0:64 offset1:80
	ds_read2st64_b32 v[164:165], v168 offset0:96 offset1:112
	s_waitcnt vmcnt(23) lgkmcnt(4)
	v_fma_f32 v6, v124, v150, v6
	v_fma_f32 v7, v124, v151, v7
	v_fma_f32 v8, v124, v152, v8
	v_fma_f32 v9, v124, v153, v9
	v_fma_f32 v2, v124, v154, v2
	v_fma_f32 v3, v124, v155, v3
	v_fma_f32 v4, v124, v156, v4
	v_fma_f32 v5, v124, v157, v5
	v_add_u32_e32 v167, 2184, v37
	ds_read2st64_b32 v[150:151], v167 offset1:16
	ds_read2st64_b32 v[152:153], v167 offset0:32 offset1:48
	ds_read2st64_b32 v[154:155], v167 offset0:64 offset1:80
	ds_read2st64_b32 v[156:157], v167 offset0:96 offset1:112
	s_waitcnt vmcnt(22) lgkmcnt(4)
	v_fma_f32 v6, v125, v158, v6
	v_fma_f32 v7, v125, v159, v7
	v_fma_f32 v8, v125, v160, v8
	v_fma_f32 v9, v125, v161, v9
	v_fma_f32 v2, v125, v162, v2
	v_fma_f32 v3, v125, v163, v3
	v_fma_f32 v4, v125, v164, v4
	v_fma_f32 v5, v125, v165, v5
	v_add_u32_e32 v168, 2268, v37
	ds_read2st64_b32 v[158:159], v168 offset1:16
	ds_read2st64_b32 v[160:161], v168 offset0:32 offset1:48
	ds_read2st64_b32 v[162:163], v168 offset0:64 offset1:80
	ds_read2st64_b32 v[164:165], v168 offset0:96 offset1:112
	s_waitcnt vmcnt(21) lgkmcnt(4)
	v_fma_f32 v6, v126, v150, v6
	v_fma_f32 v7, v126, v151, v7
	v_fma_f32 v8, v126, v152, v8
	v_fma_f32 v9, v126, v153, v9
	v_fma_f32 v2, v126, v154, v2
	v_fma_f32 v3, v126, v155, v3
	v_fma_f32 v4, v126, v156, v4
	v_fma_f32 v5, v126, v157, v5
	v_add_u32_e32 v167, 2352, v37
	ds_read2st64_b32 v[150:151], v167 offset1:16
	ds_read2st64_b32 v[152:153], v167 offset0:32 offset1:48
	ds_read2st64_b32 v[154:155], v167 offset0:64 offset1:80
	ds_read2st64_b32 v[156:157], v167 offset0:96 offset1:112
	s_waitcnt vmcnt(20) lgkmcnt(4)
	v_fma_f32 v6, v127, v158, v6
	v_fma_f32 v7, v127, v159, v7
	v_fma_f32 v8, v127, v160, v8
	v_fma_f32 v9, v127, v161, v9
	v_fma_f32 v2, v127, v162, v2
	v_fma_f32 v3, v127, v163, v3
	v_fma_f32 v4, v127, v164, v4
	v_fma_f32 v5, v127, v165, v5
	v_add_u32_e32 v168, 2436, v37
	ds_read2st64_b32 v[158:159], v168 offset1:16
	ds_read2st64_b32 v[160:161], v168 offset0:32 offset1:48
	ds_read2st64_b32 v[162:163], v168 offset0:64 offset1:80
	ds_read2st64_b32 v[164:165], v168 offset0:96 offset1:112
	s_waitcnt vmcnt(19) lgkmcnt(4)
	v_fma_f32 v6, v128, v150, v6
	v_fma_f32 v7, v128, v151, v7
	v_fma_f32 v8, v128, v152, v8
	v_fma_f32 v9, v128, v153, v9
	v_fma_f32 v2, v128, v154, v2
	v_fma_f32 v3, v128, v155, v3
	v_fma_f32 v4, v128, v156, v4
	v_fma_f32 v5, v128, v157, v5
	v_add_u32_e32 v167, 2520, v37
	ds_read2st64_b32 v[150:151], v167 offset1:16
	ds_read2st64_b32 v[152:153], v167 offset0:32 offset1:48
	ds_read2st64_b32 v[154:155], v167 offset0:64 offset1:80
	ds_read2st64_b32 v[156:157], v167 offset0:96 offset1:112
	s_waitcnt vmcnt(18) lgkmcnt(4)
	v_fma_f32 v6, v129, v158, v6
	v_fma_f32 v7, v129, v159, v7
	v_fma_f32 v8, v129, v160, v8
	v_fma_f32 v9, v129, v161, v9
	v_fma_f32 v2, v129, v162, v2
	v_fma_f32 v3, v129, v163, v3
	v_fma_f32 v4, v129, v164, v4
	v_fma_f32 v5, v129, v165, v5
	v_add_u32_e32 v168, 2604, v37
	ds_read2st64_b32 v[158:159], v168 offset1:16
	ds_read2st64_b32 v[160:161], v168 offset0:32 offset1:48
	ds_read2st64_b32 v[162:163], v168 offset0:64 offset1:80
	ds_read2st64_b32 v[164:165], v168 offset0:96 offset1:112
	s_waitcnt vmcnt(17) lgkmcnt(4)
	v_fma_f32 v6, v130, v150, v6
	v_fma_f32 v7, v130, v151, v7
	v_fma_f32 v8, v130, v152, v8
	v_fma_f32 v9, v130, v153, v9
	v_fma_f32 v2, v130, v154, v2
	v_fma_f32 v3, v130, v155, v3
	v_fma_f32 v4, v130, v156, v4
	v_fma_f32 v5, v130, v157, v5
	v_add_u32_e32 v167, 2688, v37
	ds_read2st64_b32 v[150:151], v167 offset1:16
	ds_read2st64_b32 v[152:153], v167 offset0:32 offset1:48
	ds_read2st64_b32 v[154:155], v167 offset0:64 offset1:80
	ds_read2st64_b32 v[156:157], v167 offset0:96 offset1:112
	s_waitcnt vmcnt(16) lgkmcnt(4)
	v_fma_f32 v6, v131, v158, v6
	v_fma_f32 v7, v131, v159, v7
	v_fma_f32 v8, v131, v160, v8
	v_fma_f32 v9, v131, v161, v9
	v_fma_f32 v2, v131, v162, v2
	v_fma_f32 v3, v131, v163, v3
	v_fma_f32 v4, v131, v164, v4
	v_fma_f32 v5, v131, v165, v5
	v_add_u32_e32 v168, 2772, v37
	ds_read2st64_b32 v[158:159], v168 offset1:16
	ds_read2st64_b32 v[160:161], v168 offset0:32 offset1:48
	ds_read2st64_b32 v[162:163], v168 offset0:64 offset1:80
	ds_read2st64_b32 v[164:165], v168 offset0:96 offset1:112
	s_waitcnt vmcnt(15) lgkmcnt(4)
	v_fma_f32 v6, v132, v150, v6
	v_fma_f32 v7, v132, v151, v7
	v_fma_f32 v8, v132, v152, v8
	v_fma_f32 v9, v132, v153, v9
	v_fma_f32 v2, v132, v154, v2
	v_fma_f32 v3, v132, v155, v3
	v_fma_f32 v4, v132, v156, v4
	v_fma_f32 v5, v132, v157, v5
	v_add_u32_e32 v167, 2856, v37
	ds_read2st64_b32 v[150:151], v167 offset1:16
	ds_read2st64_b32 v[152:153], v167 offset0:32 offset1:48
	ds_read2st64_b32 v[154:155], v167 offset0:64 offset1:80
	ds_read2st64_b32 v[156:157], v167 offset0:96 offset1:112
	s_waitcnt vmcnt(14) lgkmcnt(4)
	v_fma_f32 v6, v133, v158, v6
	v_fma_f32 v7, v133, v159, v7
	v_fma_f32 v8, v133, v160, v8
	v_fma_f32 v9, v133, v161, v9
	v_fma_f32 v2, v133, v162, v2
	v_fma_f32 v3, v133, v163, v3
	v_fma_f32 v4, v133, v164, v4
	v_fma_f32 v5, v133, v165, v5
	v_add_u32_e32 v168, 2940, v37
	ds_read2st64_b32 v[158:159], v168 offset1:16
	ds_read2st64_b32 v[160:161], v168 offset0:32 offset1:48
	ds_read2st64_b32 v[162:163], v168 offset0:64 offset1:80
	ds_read2st64_b32 v[164:165], v168 offset0:96 offset1:112
	s_waitcnt vmcnt(13) lgkmcnt(4)
	v_fma_f32 v6, v134, v150, v6
	v_fma_f32 v7, v134, v151, v7
	v_fma_f32 v8, v134, v152, v8
	v_fma_f32 v9, v134, v153, v9
	v_fma_f32 v2, v134, v154, v2
	v_fma_f32 v3, v134, v155, v3
	v_fma_f32 v4, v134, v156, v4
	v_fma_f32 v5, v134, v157, v5
	v_add_u32_e32 v167, 3024, v37
	ds_read2st64_b32 v[150:151], v167 offset1:16
	ds_read2st64_b32 v[152:153], v167 offset0:32 offset1:48
	ds_read2st64_b32 v[154:155], v167 offset0:64 offset1:80
	ds_read2st64_b32 v[156:157], v167 offset0:96 offset1:112
	s_waitcnt vmcnt(12) lgkmcnt(4)
	v_fma_f32 v6, v135, v158, v6
	v_fma_f32 v7, v135, v159, v7
	v_fma_f32 v8, v135, v160, v8
	v_fma_f32 v9, v135, v161, v9
	v_fma_f32 v2, v135, v162, v2
	v_fma_f32 v3, v135, v163, v3
	v_fma_f32 v4, v135, v164, v4
	v_fma_f32 v5, v135, v165, v5
	v_add_u32_e32 v168, 3108, v37
	ds_read2st64_b32 v[158:159], v168 offset1:16
	ds_read2st64_b32 v[160:161], v168 offset0:32 offset1:48
	ds_read2st64_b32 v[162:163], v168 offset0:64 offset1:80
	ds_read2st64_b32 v[164:165], v168 offset0:96 offset1:112
	s_waitcnt vmcnt(11) lgkmcnt(4)
	v_fma_f32 v6, v136, v150, v6
	v_fma_f32 v7, v136, v151, v7
	v_fma_f32 v8, v136, v152, v8
	v_fma_f32 v9, v136, v153, v9
	v_fma_f32 v2, v136, v154, v2
	v_fma_f32 v3, v136, v155, v3
	v_fma_f32 v4, v136, v156, v4
	v_fma_f32 v5, v136, v157, v5
	v_add_u32_e32 v167, 3192, v37
	ds_read2st64_b32 v[150:151], v167 offset1:16
	ds_read2st64_b32 v[152:153], v167 offset0:32 offset1:48
	ds_read2st64_b32 v[154:155], v167 offset0:64 offset1:80
	ds_read2st64_b32 v[156:157], v167 offset0:96 offset1:112
	s_waitcnt vmcnt(10) lgkmcnt(4)
	v_fma_f32 v6, v137, v158, v6
	v_fma_f32 v7, v137, v159, v7
	v_fma_f32 v8, v137, v160, v8
	v_fma_f32 v9, v137, v161, v9
	v_fma_f32 v2, v137, v162, v2
	v_fma_f32 v3, v137, v163, v3
	v_fma_f32 v4, v137, v164, v4
	v_fma_f32 v5, v137, v165, v5
	v_add_u32_e32 v168, 3276, v37
	ds_read2st64_b32 v[158:159], v168 offset1:16
	ds_read2st64_b32 v[160:161], v168 offset0:32 offset1:48
	ds_read2st64_b32 v[162:163], v168 offset0:64 offset1:80
	ds_read2st64_b32 v[164:165], v168 offset0:96 offset1:112
	s_waitcnt vmcnt(9) lgkmcnt(4)
	v_fma_f32 v6, v138, v150, v6
	v_fma_f32 v7, v138, v151, v7
	v_fma_f32 v8, v138, v152, v8
	v_fma_f32 v9, v138, v153, v9
	v_fma_f32 v2, v138, v154, v2
	v_fma_f32 v3, v138, v155, v3
	v_fma_f32 v4, v138, v156, v4
	v_fma_f32 v5, v138, v157, v5
	v_add_u32_e32 v167, 3360, v37
	ds_read2st64_b32 v[150:151], v167 offset1:16
	ds_read2st64_b32 v[152:153], v167 offset0:32 offset1:48
	ds_read2st64_b32 v[154:155], v167 offset0:64 offset1:80
	ds_read2st64_b32 v[156:157], v167 offset0:96 offset1:112
	s_waitcnt vmcnt(8) lgkmcnt(4)
	v_fma_f32 v6, v139, v158, v6
	v_fma_f32 v7, v139, v159, v7
	v_fma_f32 v8, v139, v160, v8
	v_fma_f32 v9, v139, v161, v9
	v_fma_f32 v2, v139, v162, v2
	v_fma_f32 v3, v139, v163, v3
	v_fma_f32 v4, v139, v164, v4
	v_fma_f32 v5, v139, v165, v5
	v_add_u32_e32 v168, 3444, v37
	ds_read2st64_b32 v[158:159], v168 offset1:16
	ds_read2st64_b32 v[160:161], v168 offset0:32 offset1:48
	ds_read2st64_b32 v[162:163], v168 offset0:64 offset1:80
	ds_read2st64_b32 v[164:165], v168 offset0:96 offset1:112
	s_waitcnt vmcnt(7) lgkmcnt(4)
	v_fma_f32 v6, v140, v150, v6
	v_fma_f32 v7, v140, v151, v7
	v_fma_f32 v8, v140, v152, v8
	v_fma_f32 v9, v140, v153, v9
	v_fma_f32 v2, v140, v154, v2
	v_fma_f32 v3, v140, v155, v3
	v_fma_f32 v4, v140, v156, v4
	v_fma_f32 v5, v140, v157, v5
	v_add_u32_e32 v167, 3528, v37
	ds_read2st64_b32 v[150:151], v167 offset1:16
	ds_read2st64_b32 v[152:153], v167 offset0:32 offset1:48
	ds_read2st64_b32 v[154:155], v167 offset0:64 offset1:80
	ds_read2st64_b32 v[156:157], v167 offset0:96 offset1:112
	s_waitcnt vmcnt(6) lgkmcnt(4)
	v_fma_f32 v6, v141, v158, v6
	v_fma_f32 v7, v141, v159, v7
	v_fma_f32 v8, v141, v160, v8
	v_fma_f32 v9, v141, v161, v9
	v_fma_f32 v2, v141, v162, v2
	v_fma_f32 v3, v141, v163, v3
	v_fma_f32 v4, v141, v164, v4
	v_fma_f32 v5, v141, v165, v5
	v_add_u32_e32 v168, 3612, v37
	ds_read2st64_b32 v[158:159], v168 offset1:16
	ds_read2st64_b32 v[160:161], v168 offset0:32 offset1:48
	ds_read2st64_b32 v[162:163], v168 offset0:64 offset1:80
	ds_read2st64_b32 v[164:165], v168 offset0:96 offset1:112
	s_waitcnt vmcnt(5) lgkmcnt(4)
	v_fma_f32 v6, v142, v150, v6
	v_fma_f32 v7, v142, v151, v7
	v_fma_f32 v8, v142, v152, v8
	v_fma_f32 v9, v142, v153, v9
	v_fma_f32 v2, v142, v154, v2
	v_fma_f32 v3, v142, v155, v3
	v_fma_f32 v4, v142, v156, v4
	v_fma_f32 v5, v142, v157, v5
	v_add_u32_e32 v167, 3696, v37
	ds_read2st64_b32 v[150:151], v167 offset1:16
	ds_read2st64_b32 v[152:153], v167 offset0:32 offset1:48
	ds_read2st64_b32 v[154:155], v167 offset0:64 offset1:80
	ds_read2st64_b32 v[156:157], v167 offset0:96 offset1:112
	s_waitcnt vmcnt(4) lgkmcnt(4)
	v_fma_f32 v6, v143, v158, v6
	v_fma_f32 v7, v143, v159, v7
	v_fma_f32 v8, v143, v160, v8
	v_fma_f32 v9, v143, v161, v9
	v_fma_f32 v2, v143, v162, v2
	v_fma_f32 v3, v143, v163, v3
	v_fma_f32 v4, v143, v164, v4
	v_fma_f32 v5, v143, v165, v5
	v_add_u32_e32 v168, 3780, v37
	ds_read2st64_b32 v[158:159], v168 offset1:16
	ds_read2st64_b32 v[160:161], v168 offset0:32 offset1:48
	ds_read2st64_b32 v[162:163], v168 offset0:64 offset1:80
	ds_read2st64_b32 v[164:165], v168 offset0:96 offset1:112
	s_waitcnt vmcnt(3) lgkmcnt(4)
	v_fma_f32 v6, v144, v150, v6
	v_fma_f32 v7, v144, v151, v7
	v_fma_f32 v8, v144, v152, v8
	v_fma_f32 v9, v144, v153, v9
	v_fma_f32 v2, v144, v154, v2
	v_fma_f32 v3, v144, v155, v3
	v_fma_f32 v4, v144, v156, v4
	v_fma_f32 v5, v144, v157, v5
	v_add_u32_e32 v167, 3864, v37
	ds_read2st64_b32 v[150:151], v167 offset1:16
	ds_read2st64_b32 v[152:153], v167 offset0:32 offset1:48
	ds_read2st64_b32 v[154:155], v167 offset0:64 offset1:80
	ds_read2st64_b32 v[156:157], v167 offset0:96 offset1:112
	s_waitcnt vmcnt(2) lgkmcnt(4)
	v_fma_f32 v6, v145, v158, v6
	v_fma_f32 v7, v145, v159, v7
	v_fma_f32 v8, v145, v160, v8
	v_fma_f32 v9, v145, v161, v9
	v_fma_f32 v2, v145, v162, v2
	v_fma_f32 v3, v145, v163, v3
	v_fma_f32 v4, v145, v164, v4
	v_fma_f32 v5, v145, v165, v5
	v_add_u32_e32 v168, 3948, v37
	ds_read2st64_b32 v[158:159], v168 offset1:16
	ds_read2st64_b32 v[160:161], v168 offset0:32 offset1:48
	ds_read2st64_b32 v[162:163], v168 offset0:64 offset1:80
	ds_read2st64_b32 v[164:165], v168 offset0:96 offset1:112
	s_waitcnt vmcnt(1) lgkmcnt(4)
	v_fma_f32 v6, v146, v150, v6
	v_fma_f32 v7, v146, v151, v7
	v_fma_f32 v8, v146, v152, v8
	v_fma_f32 v9, v146, v153, v9
	v_fma_f32 v2, v146, v154, v2
	v_fma_f32 v3, v146, v155, v3
	v_fma_f32 v4, v146, v156, v4
	v_fma_f32 v5, v146, v157, v5
	s_waitcnt vmcnt(0) lgkmcnt(0)
	v_fma_f32 v6, v147, v158, v6
	v_fma_f32 v7, v147, v159, v7
	v_fma_f32 v8, v147, v160, v8
	v_fma_f32 v9, v147, v161, v9
	v_fma_f32 v2, v147, v162, v2
	v_fma_f32 v3, v147, v163, v3
	v_fma_f32 v4, v147, v164, v4
	v_fma_f32 v5, v147, v165, v5
	s_and_saveexec_b64 s[6:7], s[28:29]
	s_cbranch_execz .Lp0_done
	v_add_u32_e32 v167, 4032, v37
	ds_read2st64_b32 v[150:151], v167 offset1:16
	ds_read2st64_b32 v[152:153], v167 offset0:32 offset1:48
	ds_read2st64_b32 v[154:155], v167 offset0:64 offset1:80
	ds_read2st64_b32 v[156:157], v167 offset0:96 offset1:112
	s_waitcnt vmcnt(0) lgkmcnt(0)
	v_fma_f32 v6, v148, v150, v6
	v_fma_f32 v7, v148, v151, v7
	v_fma_f32 v8, v148, v152, v8
	v_fma_f32 v9, v148, v153, v9
	v_fma_f32 v2, v148, v154, v2
	v_fma_f32 v3, v148, v155, v3
	v_fma_f32 v4, v148, v156, v4
	v_fma_f32 v5, v148, v157, v5
.Lp0_done:
	s_mov_b64 exec, s[6:7]
	ds_write_b128 v11, v[6:9] offset:32768
	ds_write_b128 v11, v[2:5] offset:32784
	s_branch .LBB0_24
	s_nop 0
	s_nop 0
	s_nop 0
	s_nop 0
	s_nop 0
	s_nop 0
	s_nop 0
	s_nop 0
	s_nop 0
	s_nop 0
	s_nop 0
	s_nop 0
	s_nop 0
	s_nop 0
	s_nop 0
	s_nop 0
	s_nop 0
	s_nop 0
	s_nop 0
	s_nop 0
	s_nop 0
	s_nop 0
	s_nop 0
	s_nop 0
	s_nop 0
	s_nop 0
	s_nop 0
	s_nop 0
	s_nop 0
	s_nop 0
	s_nop 0
	s_nop 0
	s_nop 0
	s_nop 0
	s_nop 0

.LBB0_498:
	v_add_u32_e32 v3, s85, v130
	v_and_b32_e32 v0, 0x3fffffe0, v3
	v_lshl_add_u32 v4, v0, 2, v2
	ds_read2st64_b32 v[0:1], v4 offset0:144 offset1:176
	s_mov_b64 s[78:79], 0
	s_waitcnt lgkmcnt(0)
	v_add_f32_e32 v5, v0, v1
	ds_read2st64_b32 v[0:1], v4 offset0:208 offset1:240
	s_waitcnt lgkmcnt(0)
	v_add_f32_e32 v0, v5, v0
	v_add_f32_e32 v0, v0, v1
	v_cndmask_b32_e64 v0, v0, v122, s[0:1]
	v_cndmask_b32_e32 v0, 0, v0, vcc
	v_bfe_u32 v20, v161, 0, 1
	v_bfe_u32 v21, v161, 1, 1
	v_bfe_u32 v22, v161, 2, 1
	v_bfe_u32 v23, v161, 3, 1
	v_bfe_u32 v24, v161, 4, 1
	v_mov_b32_e32 v1, 0
	ds_swizzle_b32 v8, v0 offset:0x041f
	ds_swizzle_b32 v9, v0 offset:0x081f
	ds_swizzle_b32 v10, v0 offset:0x0c1f
	ds_swizzle_b32 v11, v0 offset:0x101f
	ds_swizzle_b32 v12, v0 offset:0x141f
	ds_swizzle_b32 v13, v0 offset:0x181f
	ds_swizzle_b32 v14, v0 offset:0x1c1f
	ds_swizzle_b32 v15, v0 offset:0x201f
	ds_swizzle_b32 v16, v0 offset:0x241f
	ds_swizzle_b32 v17, v0 offset:0x281f
	ds_swizzle_b32 v18, v0 offset:0x2c1f
	ds_swizzle_b32 v19, v0 offset:0x301f
	s_waitcnt lgkmcnt(0)
	v_add_u32_e32 v8, v8, v20
	v_add_u32_e32 v9, v9, v21
	v_add_u32_e32 v10, v10, v21
	v_add_u32_e32 v11, v11, v22
	v_add_u32_e32 v12, v12, v22
	v_add_u32_e32 v13, v13, v22
	v_add_u32_e32 v14, v14, v22
	v_add_u32_e32 v15, v15, v23
	v_add_u32_e32 v16, v16, v23
	v_add_u32_e32 v17, v17, v23
	v_add_u32_e32 v18, v18, v23
	v_add_u32_e32 v19, v19, v23
	v_cmp_gt_u32_e64 s[72:73], v8, v0
	v_cmp_gt_u32_e64 s[74:75], v9, v0
	v_cmp_gt_u32_e64 s[98:99], v10, v0
	v_addc_co_u32_e64 v1, s[100:101], v1, 0, s[72:73]
	v_addc_co_u32_e64 v1, s[100:101], v1, 0, s[74:75]
	v_addc_co_u32_e64 v1, s[100:101], v1, 0, s[98:99]
	v_cmp_gt_u32_e64 s[72:73], v11, v0
	v_cmp_gt_u32_e64 s[74:75], v12, v0
	v_cmp_gt_u32_e64 s[98:99], v13, v0
	v_addc_co_u32_e64 v1, s[100:101], v1, 0, s[72:73]
	v_addc_co_u32_e64 v1, s[100:101], v1, 0, s[74:75]
	v_addc_co_u32_e64 v1, s[100:101], v1, 0, s[98:99]
	v_cmp_gt_u32_e64 s[72:73], v14, v0
	v_cmp_gt_u32_e64 s[74:75], v15, v0
	v_cmp_gt_u32_e64 s[98:99], v16, v0
	v_addc_co_u32_e64 v1, s[100:101], v1, 0, s[72:73]
	v_addc_co_u32_e64 v1, s[100:101], v1, 0, s[74:75]
	v_addc_co_u32_e64 v1, s[100:101], v1, 0, s[98:99]
	v_cmp_gt_u32_e64 s[72:73], v17, v0
	v_cmp_gt_u32_e64 s[74:75], v18, v0
	v_cmp_gt_u32_e64 s[98:99], v19, v0
	v_addc_co_u32_e64 v1, s[100:101], v1, 0, s[72:73]
	v_addc_co_u32_e64 v1, s[100:101], v1, 0, s[74:75]
	v_addc_co_u32_e64 v1, s[100:101], v1, 0, s[98:99]
	ds_swizzle_b32 v8, v0 offset:0x341f
	ds_swizzle_b32 v9, v0 offset:0x381f
	ds_swizzle_b32 v10, v0 offset:0x3c1f
	ds_swizzle_b32 v11, v0 offset:0x401f
	ds_swizzle_b32 v12, v0 offset:0x441f
	ds_swizzle_b32 v13, v0 offset:0x481f
	ds_swizzle_b32 v14, v0 offset:0x4c1f
	ds_swizzle_b32 v15, v0 offset:0x501f
	ds_swizzle_b32 v16, v0 offset:0x541f
	ds_swizzle_b32 v17, v0 offset:0x581f
	ds_swizzle_b32 v18, v0 offset:0x5c1f
	ds_swizzle_b32 v19, v0 offset:0x601f
	s_waitcnt lgkmcnt(0)
	v_add_u32_e32 v8, v8, v23
	v_add_u32_e32 v9, v9, v23
	v_add_u32_e32 v10, v10, v23
	v_add_u32_e32 v11, v11, v24
	v_add_u32_e32 v12, v12, v24
	v_add_u32_e32 v13, v13, v24
	v_add_u32_e32 v14, v14, v24
	v_add_u32_e32 v15, v15, v24
	v_add_u32_e32 v16, v16, v24
	v_add_u32_e32 v17, v17, v24
	v_add_u32_e32 v18, v18, v24
	v_add_u32_e32 v19, v19, v24
	v_cmp_gt_u32_e64 s[72:73], v8, v0
	v_cmp_gt_u32_e64 s[74:75], v9, v0
	v_cmp_gt_u32_e64 s[98:99], v10, v0
	v_addc_co_u32_e64 v1, s[100:101], v1, 0, s[72:73]
	v_addc_co_u32_e64 v1, s[100:101], v1, 0, s[74:75]
	v_addc_co_u32_e64 v1, s[100:101], v1, 0, s[98:99]
	v_cmp_gt_u32_e64 s[72:73], v11, v0
	v_cmp_gt_u32_e64 s[74:75], v12, v0
	v_cmp_gt_u32_e64 s[98:99], v13, v0
	v_addc_co_u32_e64 v1, s[100:101], v1, 0, s[72:73]
	v_addc_co_u32_e64 v1, s[100:101], v1, 0, s[74:75]
	v_addc_co_u32_e64 v1, s[100:101], v1, 0, s[98:99]
	v_cmp_gt_u32_e64 s[72:73], v14, v0
	v_cmp_gt_u32_e64 s[74:75], v15, v0
	v_cmp_gt_u32_e64 s[98:99], v16, v0
	v_addc_co_u32_e64 v1, s[100:101], v1, 0, s[72:73]
	v_addc_co_u32_e64 v1, s[100:101], v1, 0, s[74:75]
	v_addc_co_u32_e64 v1, s[100:101], v1, 0, s[98:99]
	v_cmp_gt_u32_e64 s[72:73], v17, v0
	v_cmp_gt_u32_e64 s[74:75], v18, v0
	v_cmp_gt_u32_e64 s[98:99], v19, v0
	v_addc_co_u32_e64 v1, s[100:101], v1, 0, s[72:73]
	v_addc_co_u32_e64 v1, s[100:101], v1, 0, s[74:75]
	v_addc_co_u32_e64 v1, s[100:101], v1, 0, s[98:99]
	ds_swizzle_b32 v8, v0 offset:0x641f
	ds_swizzle_b32 v9, v0 offset:0x681f
	ds_swizzle_b32 v10, v0 offset:0x6c1f
	ds_swizzle_b32 v11, v0 offset:0x701f
	ds_swizzle_b32 v12, v0 offset:0x741f
	ds_swizzle_b32 v13, v0 offset:0x781f
	ds_swizzle_b32 v14, v0 offset:0x7c1f
	s_waitcnt lgkmcnt(0)
	v_add_u32_e32 v8, v8, v24
	v_add_u32_e32 v9, v9, v24
	v_add_u32_e32 v10, v10, v24
	v_add_u32_e32 v11, v11, v24
	v_add_u32_e32 v12, v12, v24
	v_add_u32_e32 v13, v13, v24
	v_add_u32_e32 v14, v14, v24
	v_cmp_gt_u32_e64 s[72:73], v8, v0
	v_cmp_gt_u32_e64 s[74:75], v9, v0
	v_cmp_gt_u32_e64 s[98:99], v10, v0
	v_addc_co_u32_e64 v1, s[100:101], v1, 0, s[72:73]
	v_addc_co_u32_e64 v1, s[100:101], v1, 0, s[74:75]
	v_addc_co_u32_e64 v1, s[100:101], v1, 0, s[98:99]
	v_cmp_gt_u32_e64 s[72:73], v11, v0
	v_cmp_gt_u32_e64 s[74:75], v12, v0
	v_cmp_gt_u32_e64 s[98:99], v13, v0
	v_addc_co_u32_e64 v1, s[100:101], v1, 0, s[72:73]
	v_addc_co_u32_e64 v1, s[100:101], v1, 0, s[74:75]
	v_addc_co_u32_e64 v1, s[100:101], v1, 0, s[98:99]
	v_cmp_gt_u32_e64 s[72:73], v14, v0
	s_nop 1
	v_addc_co_u32_e64 v1, s[100:101], v1, 0, s[72:73]
	v_mov_b32_e32 v0, v1
	v_cmp_gt_u32_e64 s[72:73], 16, v0
	s_and_b64 s[72:73], s[72:73], vcc
	s_nop 0
	v_cndmask_b32_e64 v0, 0, 1, s[72:73]
	v_cmp_ne_u32_e64 s[74:75], 0, v0
	v_cmp_lt_i32_e64 s[72:73], 31, v59
	s_and_saveexec_b64 s[80:81], s[72:73]
	s_xor_b64 s[80:81], exec, s[80:81]
	s_cbranch_execnz .LBB0_501
	s_or_saveexec_b64 s[80:81], s[80:81]
	v_mov_b64_e32 v[0:1], s[76:77]
	s_xor_b64 exec, exec, s[80:81]
	s_cbranch_execnz .LBB0_504

.LBB0_515:
	s_waitcnt lgkmcnt(3)
	v_mfma_f32_32x32x16_bf16 v[48:63], v[100:103], v[64:67], 0
	s_waitcnt lgkmcnt(2)
	v_mfma_f32_32x32x16_bf16 v[48:63], v[96:99], v[68:71], v[48:63]
	s_waitcnt lgkmcnt(1)
	v_mfma_f32_32x32x16_bf16 v[48:63], v[92:95], v[72:75], v[48:63]
	s_waitcnt lgkmcnt(0)
	v_mfma_f32_32x32x16_bf16 v[48:63], v[88:91], v[76:79], v[48:63]
	s_nop 2
	ds_read_b128 v[32:35], v131 offset:4608
	ds_read_b128 v[88:91], v131 offset:4640
	s_waitcnt lgkmcnt(1)
	v_mfma_f32_32x32x16_bf16 v[32:47], v[32:35], v[64:67], 0
	s_waitcnt lgkmcnt(0)
	v_mfma_f32_32x32x16_bf16 v[32:47], v[88:91], v[68:71], v[32:47]
	ds_read_b128 v[88:91], v131 offset:4672
	s_waitcnt lgkmcnt(0)
	v_mfma_f32_32x32x16_bf16 v[32:47], v[88:91], v[72:75], v[32:47]
	ds_read_b128 v[88:91], v131 offset:4704
	s_waitcnt lgkmcnt(0)
	v_mfma_f32_32x32x16_bf16 v[32:47], v[88:91], v[76:79], v[32:47]
	s_and_b64 vcc, s[66:67], s[0:1]
	v_cndmask_b32_e32 v48, v120, v48, vcc
	s_and_b64 vcc, s[66:67], s[10:11]
	v_cndmask_b32_e32 v49, v120, v49, vcc
	s_and_b64 vcc, s[66:67], s[2:3]
	v_cndmask_b32_e32 v50, v120, v50, vcc
	s_and_b64 vcc, s[66:67], s[4:5]
	v_cndmask_b32_e32 v51, v120, v51, vcc
	s_and_b64 vcc, s[66:67], s[6:7]
	v_cndmask_b32_e32 v52, v120, v52, vcc
	s_and_b64 vcc, s[66:67], s[8:9]
	v_cndmask_b32_e32 v53, v120, v53, vcc
	s_and_b64 vcc, s[66:67], s[14:15]
	v_cndmask_b32_e32 v54, v120, v54, vcc
	s_and_b64 vcc, s[66:67], s[16:17]
	v_cndmask_b32_e32 v55, v120, v55, vcc
	s_and_b64 vcc, s[66:67], s[18:19]
	v_cndmask_b32_e32 v56, v120, v56, vcc
	s_and_b64 vcc, s[66:67], s[20:21]
	v_cndmask_b32_e32 v57, v120, v57, vcc
	s_and_b64 vcc, s[66:67], s[22:23]
	v_cndmask_b32_e32 v58, v120, v58, vcc
	s_and_b64 vcc, s[66:67], s[24:25]
	v_cndmask_b32_e32 v59, v120, v59, vcc
	s_and_b64 vcc, s[66:67], s[26:27]
	v_cndmask_b32_e32 v60, v120, v60, vcc
	s_and_b64 vcc, s[66:67], s[28:29]
	v_cndmask_b32_e32 v61, v120, v61, vcc
	s_and_b64 vcc, s[66:67], s[30:31]
	v_cndmask_b32_e32 v62, v120, v62, vcc
	s_and_b64 vcc, s[66:67], s[34:35]
	v_cndmask_b32_e32 v63, v120, v63, vcc
	s_and_b64 vcc, s[66:67], s[36:37]
	v_cndmask_b32_e32 v32, v120, v32, vcc
	s_and_b64 vcc, s[66:67], s[12:13]
	v_max3_f32 v88, v48, s33, v49
	v_cndmask_b32_e32 v33, v120, v33, vcc
	s_and_b64 vcc, s[66:67], s[38:39]
	v_max3_f32 v88, v88, v50, v51
	v_cndmask_b32_e32 v34, v120, v34, vcc
	s_and_b64 vcc, s[66:67], s[40:41]
	v_max3_f32 v88, v88, v52, v53
	v_cndmask_b32_e32 v35, v120, v35, vcc
	s_and_b64 vcc, s[66:67], s[42:43]
	v_max3_f32 v88, v88, v54, v55
	v_cndmask_b32_e32 v36, v120, v36, vcc
	s_and_b64 vcc, s[66:67], s[44:45]
	v_max3_f32 v88, v88, v56, v57
	v_cndmask_b32_e32 v37, v120, v37, vcc
	s_and_b64 vcc, s[66:67], s[46:47]
	v_max3_f32 v88, v88, v58, v59
	v_cndmask_b32_e32 v38, v120, v38, vcc
	s_and_b64 vcc, s[66:67], s[48:49]
	v_max3_f32 v88, v88, v60, v61
	v_cndmask_b32_e32 v39, v120, v39, vcc
	s_and_b64 vcc, s[66:67], s[50:51]
	v_max3_f32 v88, v88, v62, v63
	v_cndmask_b32_e32 v40, v120, v40, vcc
	s_and_b64 vcc, s[66:67], s[52:53]
	v_max3_f32 v88, v88, v32, v33
	v_cndmask_b32_e32 v41, v120, v41, vcc
	s_and_b64 vcc, s[66:67], s[54:55]
	v_max3_f32 v88, v88, v34, v35
	v_cndmask_b32_e32 v42, v120, v42, vcc
	s_and_b64 vcc, s[66:67], s[56:57]
	v_max3_f32 v88, v88, v36, v37
	v_cndmask_b32_e32 v43, v120, v43, vcc
	s_and_b64 vcc, s[66:67], s[58:59]
	v_max3_f32 v88, v88, v38, v39
	v_cndmask_b32_e32 v44, v120, v44, vcc
	s_and_b64 vcc, s[66:67], s[60:61]
	v_max3_f32 v88, v88, v40, v41
	v_cndmask_b32_e32 v45, v120, v45, vcc
	s_and_b64 vcc, s[66:67], s[62:63]
	v_max3_f32 v88, v88, v42, v43
	v_cndmask_b32_e32 v46, v120, v46, vcc
	s_and_b64 vcc, s[66:67], s[64:65]
	v_max3_f32 v88, v88, v44, v45
	v_cndmask_b32_e32 v47, v120, v47, vcc
	v_max3_f32 v88, v88, v46, v47
	ds_bpermute_b32 v89, v113, v88
	s_waitcnt lgkmcnt(0)
	v_max3_f32 v128, v129, v88, v89
	v_sub_f32_e32 v48, v48, v128
	v_exp_f32_e32 v88, v48
	v_sub_f32_e32 v49, v49, v128
	v_exp_f32_e32 v90, v49
	v_sub_f32_e32 v49, v50, v128
	v_exp_f32_e32 v91, v49
	v_sub_f32_e32 v49, v51, v128
	v_exp_f32_e32 v92, v49
	v_sub_f32_e32 v49, v52, v128
	v_add_f32_e32 v89, 0, v88
	v_exp_f32_e32 v93, v49
	v_sub_f32_e32 v50, v53, v128
	v_add_f32_e32 v49, v90, v89
	v_exp_f32_e32 v89, v50
	v_sub_f32_e32 v50, v54, v128
	v_add_f32_e32 v49, v91, v49
	v_exp_f32_e32 v94, v50
	v_sub_f32_e32 v50, v55, v128
	v_add_f32_e32 v49, v92, v49
	v_exp_f32_e32 v95, v50
	v_sub_f32_e32 v50, v56, v128
	v_add_f32_e32 v49, v93, v49
	v_exp_f32_e32 v96, v50
	v_sub_f32_e32 v50, v57, v128
	v_add_f32_e32 v49, v89, v49
	v_exp_f32_e32 v97, v50
	v_sub_f32_e32 v50, v58, v128
	v_add_f32_e32 v49, v94, v49
	v_exp_f32_e32 v98, v50
	v_sub_f32_e32 v50, v59, v128
	v_add_f32_e32 v49, v95, v49
	v_exp_f32_e32 v99, v50
	v_sub_f32_e32 v50, v60, v128
	v_add_f32_e32 v49, v96, v49
	v_exp_f32_e32 v100, v50
	v_sub_f32_e32 v50, v61, v128
	v_add_f32_e32 v49, v97, v49
	v_exp_f32_e32 v101, v50
	v_sub_f32_e32 v50, v62, v128
	v_add_f32_e32 v49, v98, v49
	v_exp_f32_e32 v102, v50
	v_sub_f32_e32 v50, v63, v128
	v_add_f32_e32 v49, v99, v49
	v_exp_f32_e32 v103, v50
	v_sub_f32_e32 v32, v32, v128
	v_sub_f32_e32 v48, v129, v128
	v_add_f32_e32 v49, v100, v49
	v_exp_f32_e32 v129, v32
	v_sub_f32_e32 v33, v33, v128
	v_add_f32_e32 v32, v101, v49
	v_exp_f32_e32 v131, v33
	v_sub_f32_e32 v33, v34, v128
	v_add_f32_e32 v32, v102, v32
	v_exp_f32_e32 v132, v33
	v_sub_f32_e32 v33, v35, v128
	v_add_f32_e32 v32, v103, v32
	v_exp_f32_e32 v133, v33
	v_sub_f32_e32 v33, v36, v128
	v_add_f32_e32 v32, v129, v32
	v_exp_f32_e32 v134, v33
	v_sub_f32_e32 v33, v37, v128
	v_add_f32_e32 v32, v131, v32
	v_exp_f32_e32 v135, v33
	v_sub_f32_e32 v33, v38, v128
	v_add_f32_e32 v32, v132, v32
	v_exp_f32_e32 v136, v33
	v_sub_f32_e32 v33, v39, v128
	v_add_f32_e32 v32, v133, v32
	v_exp_f32_e32 v137, v33
	v_sub_f32_e32 v33, v40, v128
	v_add_f32_e32 v32, v134, v32
	v_exp_f32_e32 v138, v33
	v_sub_f32_e32 v33, v41, v128
	v_add_f32_e32 v32, v135, v32
	v_exp_f32_e32 v139, v33
	v_sub_f32_e32 v33, v42, v128
	v_add_f32_e32 v32, v136, v32
	v_exp_f32_e32 v140, v33
	v_sub_f32_e32 v33, v43, v128
	v_add_f32_e32 v32, v137, v32
	v_exp_f32_e32 v141, v33
	v_sub_f32_e32 v33, v44, v128
	v_add_f32_e32 v32, v138, v32
	v_exp_f32_e32 v142, v33
	v_add_f32_e32 v32, v139, v32
	v_add_f32_e32 v32, v140, v32
	v_add_f32_e32 v32, v141, v32
	v_add_f32_e32 v33, v142, v32
	v_sub_f32_e32 v32, v45, v128
	v_exp_f32_e32 v143, v32
	v_sub_f32_e32 v32, v46, v128
	v_exp_f32_e32 v144, v32
	v_sub_f32_e32 v32, v47, v128
	v_exp_f32_e32 v145, v32
	v_exp_f32_e32 v32, v48
	v_add_f32_e32 v33, v143, v33
	v_add_f32_e32 v33, v144, v33
	v_add_f32_e32 v130, v145, v33
	v_pk_mul_f32 v[38:39], v[6:7], v[32:33] op_sel_hi:[1,0]
	v_pk_mul_f32 v[36:37], v[4:5], v[32:33] op_sel_hi:[1,0]
	ds_read2_b64 v[4:7], v116 offset1:2
	v_fmac_f32_e32 v130, v117, v32
	v_pk_mul_f32 v[62:63], v[30:31], v[32:33] op_sel_hi:[1,0]
	v_pk_mul_f32 v[60:61], v[28:29], v[32:33] op_sel_hi:[1,0]
	v_pk_mul_f32 v[58:59], v[26:27], v[32:33] op_sel_hi:[1,0]
	v_pk_mul_f32 v[56:57], v[24:25], v[32:33] op_sel_hi:[1,0]
	v_pk_mul_f32 v[54:55], v[22:23], v[32:33] op_sel_hi:[1,0]
	v_pk_mul_f32 v[52:53], v[20:21], v[32:33] op_sel_hi:[1,0]
	v_pk_mul_f32 v[50:51], v[18:19], v[32:33] op_sel_hi:[1,0]
	v_pk_mul_f32 v[48:49], v[16:17], v[32:33] op_sel_hi:[1,0]
	v_pk_mul_f32 v[46:47], v[14:15], v[32:33] op_sel_hi:[1,0]
	v_pk_mul_f32 v[44:45], v[12:13], v[32:33] op_sel_hi:[1,0]
	v_pk_mul_f32 v[42:43], v[10:11], v[32:33] op_sel_hi:[1,0]
	v_pk_mul_f32 v[40:41], v[8:9], v[32:33] op_sel_hi:[1,0]
	v_pk_mul_f32 v[34:35], v[2:3], v[32:33] op_sel_hi:[1,0]
	v_pk_mul_f32 v[32:33], v[0:1], v[32:33] op_sel_hi:[1,0]
	v_cvt_pk_bf16_f32 v0, v88, v90
	v_cvt_pk_bf16_f32 v1, v91, v92
	v_cvt_pk_bf16_f32 v2, v93, v89
	v_cvt_pk_bf16_f32 v3, v94, v95
	ds_read2_b64 v[16:19], v116 offset0:4 offset1:6
	v_cvt_pk_bf16_f32 v8, v96, v97
	s_waitcnt lgkmcnt(1)
	v_mfma_f32_32x32x16_bf16 v[48:63], v[4:7], v[0:3], v[48:63]
	v_cvt_pk_bf16_f32 v9, v98, v99
	v_cvt_pk_bf16_f32 v10, v100, v101
	v_cvt_pk_bf16_f32 v11, v102, v103
	v_cvt_pk_bf16_f32 v12, v129, v131
	v_cvt_pk_bf16_f32 v13, v132, v133
	v_cvt_pk_bf16_f32 v14, v134, v135
	v_cvt_pk_bf16_f32 v15, v136, v137
	s_waitcnt lgkmcnt(0)
	v_mfma_f32_32x32x16_bf16 v[48:63], v[16:19], v[8:11], v[48:63]
	v_cvt_pk_bf16_f32 v4, v138, v139
	v_cvt_pk_bf16_f32 v5, v140, v141
	v_cvt_pk_bf16_f32 v6, v142, v143
	v_cvt_pk_bf16_f32 v7, v144, v145
	ds_read2_b64 v[16:19], v116 offset0:8 offset1:10
	s_waitcnt lgkmcnt(0)
	v_mfma_f32_32x32x16_bf16 v[48:63], v[16:19], v[12:15], v[48:63]
	ds_read2_b64 v[16:19], v116 offset0:12 offset1:14
	s_waitcnt lgkmcnt(0)
	v_mfma_f32_32x32x16_bf16 v[48:63], v[16:19], v[4:7], v[48:63]
	ds_read2_b64 v[16:19], v111 offset0:64 offset1:66
	s_waitcnt lgkmcnt(0)
	v_mfma_f32_32x32x16_bf16 v[32:47], v[16:19], v[0:3], v[32:47]
	ds_read2_b64 v[0:3], v111 offset0:68 offset1:70
	s_waitcnt lgkmcnt(0)
	v_mfma_f32_32x32x16_bf16 v[32:47], v[0:3], v[8:11], v[32:47]
	ds_read2_b64 v[0:3], v111 offset0:72 offset1:74
	s_waitcnt lgkmcnt(0)
	v_mfma_f32_32x32x16_bf16 v[32:47], v[0:3], v[12:15], v[32:47]
	ds_read2_b64 v[0:3], v111 offset0:76 offset1:78
	s_waitcnt lgkmcnt(0)
	v_mfma_f32_32x32x16_bf16 v[32:47], v[0:3], v[4:7], v[32:47]
	s_andn2_b64 vcc, exec, s[68:69]
	s_xor_b32 s73, s73, 1
	s_cbranch_vccz .LBB0_511
	s_branch .LBB0_512
	s_nop 0
	s_nop 0
	s_nop 0

	.amdhsa_kernel _Z14fwd_megakernel4Args
		.amdhsa_group_segment_fixed_size 0
		.amdhsa_private_segment_fixed_size 0
		.amdhsa_kernarg_size 432
		.amdhsa_user_sgpr_count 2
		.amdhsa_user_sgpr_dispatch_ptr 0
		.amdhsa_user_sgpr_queue_ptr 0
		.amdhsa_user_sgpr_kernarg_segment_ptr 1
		.amdhsa_user_sgpr_dispatch_id 0
		.amdhsa_user_sgpr_kernarg_preload_length 0
		.amdhsa_user_sgpr_kernarg_preload_offset 0
		.amdhsa_user_sgpr_private_segment_size 0
		.amdhsa_uses_dynamic_stack 0
		.amdhsa_enable_private_segment 0
		.amdhsa_system_sgpr_workgroup_id_x 1
		.amdhsa_system_sgpr_workgroup_id_y 0
		.amdhsa_system_sgpr_workgroup_id_z 0
		.amdhsa_system_sgpr_workgroup_info 0
		.amdhsa_system_vgpr_workitem_id 2
		.amdhsa_next_free_vgpr 248
		.amdhsa_next_free_sgpr 102
		.amdhsa_accum_offset 248
		.amdhsa_reserve_vcc 1
		.amdhsa_float_round_mode_32 0
		.amdhsa_float_round_mode_16_64 0
		.amdhsa_float_denorm_mode_32 3
		.amdhsa_float_denorm_mode_16_64 3
		.amdhsa_dx10_clamp 1
		.amdhsa_ieee_mode 1
		.amdhsa_fp16_overflow 0
		.amdhsa_tg_split 0
		.amdhsa_exception_fp_ieee_invalid_op 0
		.amdhsa_exception_fp_denorm_src 0
		.amdhsa_exception_fp_ieee_div_zero 0
		.amdhsa_exception_fp_ieee_overflow 0
		.amdhsa_exception_fp_ieee_underflow 0
		.amdhsa_exception_fp_ieee_inexact 0
		.amdhsa_exception_int_div_zero 0
	.end_amdhsa_kernel

amdhsa.kernels:
  - .agpr_count:     0
    .args:
      - .offset:         0
        .size:           176
        .value_kind:     by_value
      - .offset:         176
        .size:           4
        .value_kind:     hidden_block_count_x
      - .offset:         180
        .size:           4
        .value_kind:     hidden_block_count_y
      - .offset:         184
        .size:           4
        .value_kind:     hidden_block_count_z
      - .offset:         188
        .size:           2
        .value_kind:     hidden_group_size_x
      - .offset:         190
        .size:           2
        .value_kind:     hidden_group_size_y
      - .offset:         192
        .size:           2
        .value_kind:     hidden_group_size_z
      - .offset:         194
        .size:           2
        .value_kind:     hidden_remainder_x
      - .offset:         196
        .size:           2
        .value_kind:     hidden_remainder_y
      - .offset:         198
        .size:           2
        .value_kind:     hidden_remainder_z
      - .offset:         216
        .size:           8
        .value_kind:     hidden_global_offset_x
      - .offset:         224
        .size:           8
        .value_kind:     hidden_global_offset_y
      - .offset:         232
        .size:           8
        .value_kind:     hidden_global_offset_z
      - .offset:         240
        .size:           2
        .value_kind:     hidden_grid_dims
      - .offset:         264
        .size:           8
        .value_kind:     hidden_multigrid_sync_arg
      - .offset:         296
        .size:           4
        .value_kind:     hidden_dynamic_lds_size
    .group_segment_fixed_size: 0
    .kernarg_segment_align: 8
    .kernarg_segment_size: 432
    .language:       OpenCL C
    .language_version:
      - 2
      - 0
    .max_flat_workgroup_size: 512
    .name:           _Z14fwd_megakernel4Args
    .private_segment_fixed_size: 0
    .sgpr_count:     108
    .sgpr_spill_count: 120
    .symbol:         _Z14fwd_megakernel4Args.kd
    .uniform_work_group_size: 1
    .uses_dynamic_stack: false
    .vgpr_count:     248
    .vgpr_spill_count: 0
    .wavefront_size: 64
